# odin GEMM: column-tile pair rotated by round (tn2 + 4*round mod 16) so each workgroup gets a mix of epilogue types instead of four units of one type
# speedup vs baseline: 1.0062x; 1.0055x over previous
.LBB0_451:
	s_or_b64 exec, exec, s[2:3]
	s_and_b64 vcc, exec, s[0:1]
	v_readlane_b32 s0, v254, 44
	v_readlane_b32 s1, v254, 45
	s_mov_b64 s[2:3], -1
	s_waitcnt lgkmcnt(0)
	v_cndmask_b32_e64 v1, 0, 1, s[0:1]
	v_cmp_ne_u32_e64 s[0:1], 1, v1
	s_barrier
	.p2align 8
	s_nop 0
	v_writelane_b32 v255, s0, 24
	s_nop 1
	v_writelane_b32 v255, s1, 25
	s_cbranch_vccz .LBB0_869
	s_load_dwordx2 s[0:1], s[58:59], 0xe0
	v_readlane_b32 s4, v255, 24
	v_readlane_b32 s5, v255, 25
	s_movk_i32 s93, 0x70
	s_and_b64 vcc, exec, s[4:5]
	s_cbranch_vccnz .LBB0_496
	s_waitcnt lgkmcnt(0)
	s_add_u32 s14, s0, 0x9dd8800
	s_addc_u32 s15, s1, 0
	s_add_u32 s24, s0, 0x1c20000
	s_addc_u32 s34, s1, 0
	s_add_u32 s16, s0, 0x9cd8800
	s_addc_u32 s17, s1, 0
	s_add_u32 s18, s0, 0x9d58800
	s_addc_u32 s19, s1, 0
	s_add_u32 s42, s0, 0x1c20080
	s_addc_u32 s43, s1, 0
	s_add_u32 s20, s0, 0x9dd8880
	s_addc_u32 s21, s1, 0
	s_add_u32 s22, s0, 0x13dd8800
	s_addc_u32 s23, s1, 0
	s_add_u32 s44, s0, 0x12dd8800
	s_load_dwordx2 s[12:13], s[58:59], 0xb0
	s_addc_u32 s45, s1, 0
	s_add_u32 s46, s0, 0x11dd8800
	s_addc_u32 s47, s1, 0
	s_add_u32 s48, s0, 0xddd8800
	s_addc_u32 s49, s1, 0
	s_mov_b32 m0, s92
	s_lshr_b32 s2, m0, 9
	s_lshl_b32 s2, s2, 2
	s_add_i32 s2, s2, m0
	s_and_b32 s2, s2, 15
	s_andn2_b32 s68, m0, 15
	s_or_b32 s68, s68, s2
	s_mov_b32 s59, s68
	s_lshl_b32 s58, s68, 3
	s_branch .LBB0_455
.LBB0_454:
	s_add_i32 m0, m0, s94
	s_lshr_b32 s2, m0, 9
	s_lshl_b32 s2, s2, 2
	s_add_i32 s2, s2, m0
	s_and_b32 s2, s2, 15
	s_andn2_b32 s68, m0, 15
	s_or_b32 s68, s68, s2
	s_mov_b32 s59, s68
	s_lshl_b32 s58, s68, 3
	v_readlane_b32 s76, v255, 15
	s_cmp_gt_i32 m0, 0x7ff
	v_readlane_b32 s77, v255, 16
	s_cbranch_scc1 .LBB0_496
